# sample attention: loads for the tile two ahead are issued at the end of each step (a whole step of flight time) instead of at the start of the consuming step
# baseline (speedup 1.0000x reference)
; __device__ __forceinline__ void sattn_unit(const Args& a, LAS unsigned char* lds, const LAS float* bt, int db, int h, int t, int tid, int wave, int lane) {
;     ...
;     for (int it = 0; it < nf; ++it) {
;         const int key0 = __builtin_amdgcn_readfirstlane((tile0 + it) * 32);
;         bf16x8 kf[4]; bf16x8 vf[2][2];
;         SA_CVT();
;         if (it + 1 < nf) SA_LOAD(key0 + 32);
.LBB0_295:
	ds_write_b128 v172, v[64:67] offset:40960
	ds_write_b128 v172, v[68:71] offset:42048
	s_waitcnt lgkmcnt(0)
	s_barrier
	ds_read_b64_tr_b16 v[72:73], v249
	ds_read_b64_tr_b16 v[74:75], v249 offset:512
	ds_read_b64_tr_b16 v[76:77], v249 offset:1024
	ds_read_b64_tr_b16 v[78:79], v249 offset:1536
	ds_read_b64_tr_b16 v[80:81], v249 offset:2048
	ds_read_b64_tr_b16 v[82:83], v249 offset:2560
	ds_read_b64_tr_b16 v[84:85], v249 offset:3072
	ds_read_b64_tr_b16 v[86:87], v249 offset:3584
	ds_read_b128 v[108:111], v170 offset:40960
	ds_read_b128 v[104:107], v170 offset:40976
	ds_read_b128 v[100:103], v170 offset:41024
	ds_read_b128 v[96:99], v170 offset:41040
	ds_read_b128 v[44:47], v170 offset:41088
	ds_read_b128 v[40:43], v170 offset:41104
	ds_read_b128 v[36:39], v170 offset:41152
	ds_read_b128 v[32:35], v170 offset:41168
	v_add_u32_e32 v170, s32, v170
	v_add_u32_e32 v172, s32, v172
	s_sub_i32 s32, 0, s32
	v_add_u32_e32 v249, s34, v249
	v_add_u32_e32 v248, s34, v248
	s_sub_i32 s34, 0, s34
	s_add_i32 s0, s96, s35
	s_lshl_b32 vcc_lo, s0, 5
	s_add_i32 s35, s35, 1
	s_cmp_lg_u32 s35, 1
	s_cbranch_scc1 .LBB0_297
	s_add_i32 s0, s30, vcc_lo
	s_ashr_i32 s1, s0, 31
	s_lshl_b64 s[0:1], s[0:1], 12
	s_lshl_b32 s14, s5, 2
	s_or_b32 s0, s0, s14
	s_add_u32 s48, s93, s0
	s_addc_u32 s49, s89, s1
	s_add_u32 s48, s48, s81
	s_addc_u32 s49, s49, 0
	s_add_u32 s0, s42, s0
	s_addc_u32 s1, s43, s1
	v_lshl_add_u64 v[212:213], v[112:113], 2, s[48:49]
	v_lshl_add_u64 v[216:217], v[120:121], 2, s[48:49]
	global_load_dwordx4 v[212:215], v[212:213], off
	s_nop 0
	global_load_dwordx4 v[216:219], v[216:217], off
	s_nop 0
	global_load_dwordx4 v[196:199], v250, s[0:1]
	s_add_u32 s14, s0, 0x2000
	s_addc_u32 s15, s1, 0
	global_load_dwordx4 v[200:203], v250, s[14:15]
	s_add_u32 s48, s0, 0x4000
	s_addc_u32 s49, s1, 0
	global_load_dwordx4 v[204:207], v250, s[48:49]
	s_add_u32 s14, s0, 0x6000
	s_addc_u32 s15, s1, 0
	global_load_dwordx4 v[208:211], v250, s[14:15]

; __device__ __forceinline__ void sattn_unit(const Args& a, LAS unsigned char* lds, const LAS float* bt, int db, int h, int t, int tid, int wave, int lane) {
;     ...
;     for (int it = 0; it < nf; ++it) {
;         const int key0 = __builtin_amdgcn_readfirstlane((tile0 + it) * 32);
;         bf16x8 kf[4]; bf16x8 vf[2][2];
;         SA_CVT();
;         if (it + 1 < nf) SA_LOAD(key0 + 32);
.LBB0_301:
	v_sub_f32_e32 v32, v32, v104
	v_exp_f32_e32 v32, v32
	v_sub_f32_e32 v33, v33, v104
	v_exp_f32_e32 v33, v33
	v_sub_f32_e32 v34, v34, v104
	v_exp_f32_e32 v34, v34
	v_sub_f32_e32 v35, v35, v104
	v_sub_f32_e32 v36, v36, v104
	v_sub_f32_e32 v37, v37, v104
	v_sub_f32_e32 v38, v38, v104
	v_sub_f32_e32 v39, v39, v104
	v_exp_f32_e32 v35, v35
	v_exp_f32_e32 v36, v36
	v_exp_f32_e32 v37, v37
	v_exp_f32_e32 v38, v38
	v_exp_f32_e32 v39, v39
	v_add_f32_e32 v105, 0, v32
	v_add_f32_e32 v105, v33, v105
	v_add_f32_e32 v105, v34, v105
	v_add_f32_e32 v105, v35, v105
	v_cvt_pk_bf16_f32 v32, v32, v33
	v_cvt_pk_bf16_f32 v33, v34, v35
	v_cvt_pk_bf16_f32 v34, v36, v37
	v_cvt_pk_bf16_f32 v35, v38, v39
	v_sub_f32_e32 v40, v40, v104
	v_sub_f32_e32 v41, v41, v104
	v_sub_f32_e32 v42, v42, v104
	v_sub_f32_e32 v43, v43, v104
	v_sub_f32_e32 v44, v44, v104
	v_sub_f32_e32 v45, v45, v104
	v_sub_f32_e32 v46, v46, v104
	v_sub_f32_e32 v47, v47, v104
	v_exp_f32_e32 v40, v40
	v_exp_f32_e32 v41, v41
	v_exp_f32_e32 v42, v42
	v_exp_f32_e32 v43, v43
	v_exp_f32_e32 v44, v44
	v_exp_f32_e32 v45, v45
	v_exp_f32_e32 v46, v46
	v_exp_f32_e32 v47, v47
	v_add_f32_e32 v105, v36, v105
	v_mfma_f32_32x32x16_bf16 v[0:15], v[32:35], v[72:75], v[0:15]
	v_add_f32_e32 v105, v37, v105
	v_add_f32_e32 v105, v38, v105
	v_add_f32_e32 v105, v39, v105
	v_cvt_pk_bf16_f32 v36, v40, v41
	v_cvt_pk_bf16_f32 v37, v42, v43
	v_cvt_pk_bf16_f32 v38, v44, v45
	v_cvt_pk_bf16_f32 v39, v46, v47
	v_mfma_f32_32x32x16_bf16 v[16:31], v[32:35], v[80:83], v[16:31]
	v_add_f32_e32 v105, v40, v105
	v_add_f32_e32 v105, v41, v105
	v_mfma_f32_32x32x16_bf16 v[0:15], v[36:39], v[76:79], v[0:15]
	v_add_f32_e32 v105, v42, v105
	v_add_f32_e32 v105, v43, v105
	v_add_f32_e32 v105, v44, v105
	v_add_f32_e32 v105, v45, v105
	v_add_f32_e32 v105, v46, v105
	v_add_f32_e32 v105, v47, v105
	v_add_f32_e32 v169, v105, v169
	v_mfma_f32_32x32x16_bf16 v[16:31], v[36:39], v[84:87], v[16:31]
	s_cmp_eq_u32 s97, s35
	s_cbranch_scc1 .LBB0_303
	s_waitcnt vmcnt(0)
	v_mov_b32_e32 v64, v212
	v_mov_b32_e32 v65, v213
	v_mov_b32_e32 v66, v214
	v_mov_b32_e32 v67, v215
	v_mov_b32_e32 v68, v216
	v_mov_b32_e32 v69, v217
	v_mov_b32_e32 v70, v218
	v_mov_b32_e32 v71, v219
	v_cvt_pk_bf16_f32 v88, v196, v197
	v_cvt_pk_bf16_f32 v89, v198, v199
	v_cvt_pk_bf16_f32 v90, v200, v201
	v_cvt_pk_bf16_f32 v91, v202, v203
	v_cvt_pk_bf16_f32 v92, v204, v205
	v_cvt_pk_bf16_f32 v93, v206, v207
	v_cvt_pk_bf16_f32 v94, v208, v209
	v_cvt_pk_bf16_f32 v95, v210, v211
	ds_write_b64 v248, v[88:89]
	ds_write_b64 v248, v[90:91] offset:128
	ds_write_b64 v248, v[92:93] offset:256
	ds_write_b64 v248, v[94:95] offset:384
	s_add_i32 s14, s35, 1
	s_cmp_ge_u32 s14, s97
	s_cbranch_scc1 .Lsa_nold
	s_add_i32 s0, s96, s35
	s_lshl_b32 s14, s0, 5
	s_add_i32 s0, s30, s14
	s_ashr_i32 s1, s0, 31
	s_lshl_b64 s[0:1], s[0:1], 12
	s_lshl_b32 s14, s5, 2
	s_or_b32 s0, s0, s14
	s_add_u32 s48, s93, s0
	s_addc_u32 s49, s89, s1
	s_add_u32 s48, s48, s81
	s_addc_u32 s49, s49, 0
	s_add_u32 s0, s42, s0
	s_addc_u32 s1, s43, s1
	v_lshl_add_u64 v[212:213], v[112:113], 2, s[48:49]
	v_lshl_add_u64 v[216:217], v[120:121], 2, s[48:49]
	global_load_dwordx4 v[212:215], v[212:213], off
	s_nop 0
	global_load_dwordx4 v[216:219], v[216:217], off
	s_nop 0
	global_load_dwordx4 v[196:199], v250, s[0:1]
	s_add_u32 s14, s0, 0x2000
	s_addc_u32 s15, s1, 0
	global_load_dwordx4 v[200:203], v250, s[14:15]
	s_add_u32 s48, s0, 0x4000
	s_addc_u32 s49, s1, 0
	global_load_dwordx4 v[204:207], v250, s[48:49]
	s_add_u32 s14, s0, 0x6000
	s_addc_u32 s15, s1, 0
	global_load_dwordx4 v[208:211], v250, s[14:15]
.Lsa_nold:
	v_mov_b32_e32 v244, v104
	s_branch .LBB0_295
